# S5 pass 1: B*u for 32 steps at a time on the f32 matrix core (v_mfma_f32_32x32x2_f32, same fma order), lane=state via permlane32 swaps; plus window fast path
# speedup vs baseline: 1.0150x; 1.0150x over previous
; template <int PASS>
; __device__ __forceinline__ void s5_task(CArgs* Ap, int l, int b, int g, int c, LAS unsigned char* wl, int lane) {
;     ...
;     const float a_re = fminf(Ap->in[6][(l * NGRP + g) * NST + p], -1e-4f), a_im = Ap->in[7][(l * NGRP + g) * NST + p];
;     const float dt = expf(Ap->in[8][l * NGRP + g]);
;     const float mag = expf(a_re * dt); float sn, cs; sincos_small(a_im * dt, sn, cs);
;     const float ab_re = mag * cs, ab_im = mag * sn;
;     const float nr = ab_re - 1.f, ni = ab_im, den = a_re * a_re + a_im * a_im;
;     const float f_re = (nr * a_re + ni * a_im) / den, f_im = (ni * a_re - nr * a_im) / den;
;     float bbr[16], bbi[16]; f32x2 bb2[16];
;     {
;         const f32x4* br = (const f32x4*)(Ap->in[9] + ((size_t)(l * NGRP + g) * NST + p) * 16); const f32x4* bi = (const f32x4*)(Ap->in[10] + ((size_t)(l * NGRP + g) * NST + p) * 16);
; #pragma unroll
;         for (int q = 0; q < 4; ++q) { const f32x4 vr = br[q], vi = bi[q];
; #pragma unroll
;             for (int i = 0; i < 4; ++i) { bbr[4 * q + i] = f_re * vr[i] - f_im * vi[i]; bbi[4 * q + i] = f_re * vi[i] + f_im * vr[i]; bb2[4 * q + i] = (f32x2){bbr[4 * q + i], bbi[4 * q + i]}; } }
;     ...
;     const size_t row0 = (size_t)b * SEQ + (size_t)c * CHUNK;
;     const bf16_t* up = P + (row0 + (lane >> 2)) * NINP + g * 16 + 4 * (lane & 3);
;     u32x2 unext = *(const u32x2*)up;
.LBB0_823:
	s_or_b64 exec, exec, s[6:7]
	s_load_dwordx4 s[20:23], s[0:1], 0x48
	s_waitcnt vmcnt(0)
	v_max_f32_e32 v2, v2, v2
	v_min_f32_e32 v18, 0xb8d1b717, v2
	v_mul_f32_e32 v9, v18, v3
	s_lshl_b64 s[6:7], s[72:73], 12
	v_mul_f32_e32 v11, 0x3fb8aa3b, v9
	v_lshl_or_b32 v2, v6, 2, s6
	v_mov_b32_e32 v3, s7
	s_mov_b32 s3, 0x3fb8aa3b
	s_waitcnt lgkmcnt(0)
	v_lshl_add_u64 v[20:21], s[20:21], 0, v[2:3]
	v_lshl_add_u64 v[42:43], s[22:23], 0, v[2:3]
	v_fma_f32 v2, v9, s3, -v11
	v_rndne_f32_e32 v3, v11
	v_fmac_f32_e32 v2, 0x32a5705f, v9
	v_sub_f32_e32 v11, v11, v3
	v_add_f32_e32 v2, v11, v2
	v_exp_f32_e32 v2, v2
	v_cvt_i32_f32_e32 v3, v3
	s_mov_b32 s3, 0xc2ce8ed0
	v_cmp_ngt_f32_e32 vcc, s3, v9
	s_mov_b32 s3, 0x42b17218
	v_ldexp_f32 v2, v2, v3
	v_cndmask_b32_e32 v2, 0, v2, vcc
	v_cmp_nlt_f32_e32 vcc, s3, v9
	global_load_dwordx4 v[22:25], v[42:43], off
	global_load_dwordx4 v[26:29], v[20:21], off
	v_cndmask_b32_e32 v2, v179, v2, vcc
	global_load_dwordx4 v[30:33], v[20:21], off offset:16
	global_load_dwordx4 v[34:37], v[42:43], off offset:16
	v_mul_f32_e32 v14, v2, v1
	v_mul_f32_e32 v17, v2, v0
	v_fma_f32 v16, v2, v1, -1.0
	global_load_dwordx4 v[0:3], v[20:21], off offset:48
	global_load_dwordx4 v[38:41], v[20:21], off offset:32
	v_mov_b32_e32 v20, v19
	v_pk_mul_f32 v[44:45], v[18:19], v[18:19]
	v_pk_mul_f32 v[20:21], v[20:21], v[16:17] op_sel:[0,1] op_sel_hi:[0,0]
	v_pk_fma_f32 v[52:53], v[18:19], v[16:17], v[20:21] op_sel_hi:[0,1,1] neg_lo:[0,0,1] neg_hi:[0,0,1]
	v_pk_add_f32 v[54:55], v[44:45], v[44:45] op_sel:[0,1] op_sel_hi:[0,1]
	v_div_scale_f32 v9, s[8:9], v55, v55, v53
	v_rcp_f32_e32 v11, v9
	v_pk_fma_f32 v[18:19], v[18:19], v[16:17], v[20:21]
	global_load_dwordx4 v[44:47], v[42:43], off offset:48
	global_load_dwordx4 v[48:51], v[42:43], off offset:32
	s_ashr_i32 s6, s14, 7
	v_fma_f32 v13, -v9, v11, 1.0
	v_fmac_f32_e32 v11, v13, v11
	v_div_scale_f32 v13, vcc, v53, v55, v53
	v_mul_f32_e32 v15, v13, v11
	v_fma_f32 v16, -v9, v15, v13
	v_fmac_f32_e32 v15, v16, v11
	v_fma_f32 v9, -v9, v15, v13
	v_div_scale_f32 v13, s[8:9], v54, v54, v18
	v_rcp_f32_e32 v16, v13
	v_div_fmas_f32 v9, v9, v11, v15
	v_div_fixup_f32 v55, v9, v55, v53
	s_ashr_i32 s7, s6, 31
	v_fma_f32 v9, -v13, v16, 1.0
	v_fmac_f32_e32 v16, v9, v16
	v_div_scale_f32 v9, vcc, v18, v54, v18
	v_mul_f32_e32 v11, v9, v16
	v_fma_f32 v15, -v13, v11, v9
	v_fmac_f32_e32 v11, v15, v16
	s_ashr_i32 s3, s2, 31
	v_fma_f32 v9, -v13, v11, v9
	s_lshl_b64 s[8:9], s[6:7], 13
	s_lshl_b64 s[20:21], s[2:3], 9
	v_div_fmas_f32 v9, v9, v16, v11
	s_add_u32 s3, s20, s8
	v_div_fixup_f32 v54, v9, v54, v18
	v_or_b32_e32 v9, s3, v8
	v_mov_b64_e32 v[18:19], s[4:5]
	s_addc_u32 s7, s21, s9
	v_mad_u64_u32 v[18:19], s[8:9], v9, s79, v[18:19]
	v_mad_i32_i24 v19, s7, v180, v19
	s_lshl_b32 s72, s15, 5
	v_lshl_add_u64 v[18:19], v[18:19], 0, s[72:73]
	v_mov_b32_e32 v11, v145
	v_lshl_add_u64 v[56:57], v[18:19], 0, v[10:11]
	v_add_co_u32_e32 v18, vcc, 0x1ba00000, v56
	v_mov_b32_e32 v144, v145
	s_nop 0
	v_addc_co_u32_e32 v19, vcc, 0, v57, vcc
	global_load_dwordx2 v[52:53], v[18:19], off
	s_lshl_b32 s3, s15, 4
	s_mov_b32 s7, 0
	v_mov_b32_e32 v15, v14
	s_waitcnt vmcnt(8)
	v_pk_mul_f32 v[20:21], v[54:55], v[22:23] op_sel:[1,0] op_sel_hi:[0,0]
	s_waitcnt vmcnt(7)
	v_pk_fma_f32 v[18:19], v[26:27], v[54:55], v[20:21] neg_lo:[0,0,1] neg_hi:[0,0,1]
	v_pk_fma_f32 v[20:21], v[26:27], v[54:55], v[20:21] op_sel_hi:[0,1,1]
	v_pk_mul_f32 v[22:23], v[54:55], v[22:23] op_sel:[1,1] op_sel_hi:[0,1]
	v_mov_b32_e32 v19, v21
	v_pk_fma_f32 v[20:21], v[26:27], v[54:55], v[22:23] op_sel:[1,0,0] neg_lo:[0,0,1] neg_hi:[0,0,1]
	v_pk_fma_f32 v[22:23], v[26:27], v[54:55], v[22:23] op_sel:[1,0,0]
	v_pk_mul_f32 v[26:27], v[54:55], v[24:25] op_sel:[1,0] op_sel_hi:[0,0]
	v_mov_b32_e32 v21, v23
	v_pk_fma_f32 v[22:23], v[28:29], v[54:55], v[26:27] neg_lo:[0,0,1] neg_hi:[0,0,1]
	v_pk_fma_f32 v[26:27], v[28:29], v[54:55], v[26:27] op_sel_hi:[0,1,1]
	v_mov_b32_e32 v16, v25
	v_mov_b32_e32 v23, v27
	v_pk_mul_f32 v[26:27], v[54:55], v[16:17] op_sel:[1,0] op_sel_hi:[0,0]
	v_mov_b32_e32 v16, v29
	v_pk_fma_f32 v[24:25], v[16:17], v[54:55], v[26:27] op_sel_hi:[0,1,1] neg_lo:[0,0,1] neg_hi:[0,0,1]
	v_pk_fma_f32 v[26:27], v[16:17], v[54:55], v[26:27] op_sel_hi:[0,1,1]
	s_waitcnt vmcnt(5)
	v_pk_mul_f32 v[28:29], v[54:55], v[34:35] op_sel:[1,0] op_sel_hi:[0,0]
	v_mov_b32_e32 v25, v27
	v_pk_fma_f32 v[26:27], v[54:55], v[30:31], v[28:29] neg_lo:[0,0,1] neg_hi:[0,0,1]
	v_pk_fma_f32 v[28:29], v[54:55], v[30:31], v[28:29] op_sel_hi:[1,0,1]
	v_pk_mul_f32 v[34:35], v[54:55], v[34:35] op_sel:[1,1] op_sel_hi:[0,1]
	v_mov_b32_e32 v27, v29
	v_pk_fma_f32 v[28:29], v[54:55], v[30:31], v[34:35] op_sel:[0,1,0] neg_lo:[0,0,1] neg_hi:[0,0,1]
	v_pk_fma_f32 v[30:31], v[54:55], v[30:31], v[34:35] op_sel:[0,1,0]
	v_pk_mul_f32 v[34:35], v[54:55], v[36:37] op_sel:[1,0] op_sel_hi:[0,0]
	v_mov_b32_e32 v29, v31
	v_pk_fma_f32 v[30:31], v[54:55], v[32:33], v[34:35] neg_lo:[0,0,1] neg_hi:[0,0,1]
	v_pk_fma_f32 v[34:35], v[54:55], v[32:33], v[34:35] op_sel_hi:[1,0,1]
	v_mov_b32_e32 v16, v37
	v_mov_b32_e32 v31, v35
	v_pk_mul_f32 v[34:35], v[54:55], v[16:17] op_sel:[1,0] op_sel_hi:[0,0]
	v_mov_b32_e32 v16, v33
	v_pk_fma_f32 v[32:33], v[54:55], v[16:17], v[34:35] op_sel_hi:[1,0,1] neg_lo:[0,0,1] neg_hi:[0,0,1]
	v_pk_fma_f32 v[34:35], v[54:55], v[16:17], v[34:35] op_sel_hi:[1,0,1]
	s_waitcnt vmcnt(1)
; #define LAS __attribute__((address_space(3)))
; __device__ __forceinline__ float bflo(unsigned w) { return __uint_as_float(w << 16); }
; __device__ __forceinline__ float bfhi(unsigned w) { return __uint_as_float(w & 0xffff0000u); }
; __device__ __forceinline__ void wave_lds_fence() { asm volatile("s_waitcnt lgkmcnt(0)" ::: "memory"); }
; template <int PASS>
; __device__ __forceinline__ void s5_task(CArgs* Ap, int l, int b, int g, int c, LAS unsigned char* wl, int lane) {
;     ...
;         for (int q = 0; q < 4; ++q) { const f32x4 vr = br[q], vi = bi[q];
; #pragma unroll
;             for (int i = 0; i < 4; ++i) { bbr[4 * q + i] = f_re * vr[i] - f_im * vi[i]; bbi[4 * q + i] = f_re * vi[i] + f_im * vr[i]; bb2[4 * q + i] = (f32x2){bbr[4 * q + i], bbi[4 * q + i]}; } }
;     ...
;     const bf16_t* up = P + (row0 + (lane >> 2)) * NINP + g * 16 + 4 * (lane & 3);
;     u32x2 unext = *(const u32x2*)up;
;     bf16_t* Y1 = (bf16_t*)(ws + WS_Y1);
;     for (int tb = 0; tb < CHUNK; tb += 16) {
;         const u32x2 ucur = unext;
;         if (tb + 16 < CHUNK) unext = *(const u32x2*)(up + (size_t)(tb + 16) * NINP);
;         *(LAS f32x4*)(us + (lane >> 2) * 16 + 4 * (lane & 3)) = (f32x4){bflo(ucur.x), bfhi(ucur.x), bflo(ucur.y), bfhi(ucur.y)};
;         wave_lds_fence();
; #pragma unroll 4
;         for (int s = 0; s < 16; ++s) {
;             const f32x4 u0 = *(const LAS f32x4*)(us + s * 16), u1 = *(const LAS f32x4*)(us + s * 16 + 4), u2 = *(const LAS f32x4*)(us + s * 16 + 8), u3 = *(const LAS f32x4*)(us + s * 16 + 12);
;             f32x2 bu = (f32x2){0.f, 0.f};
; #pragma unroll
;             for (int i = 0; i < 4; ++i) bu = bb2[i] * (f32x2){u0[i], u0[i]} + bu;
; #pragma unroll
;             for (int i = 0; i < 4; ++i) bu = bb2[4 + i] * (f32x2){u1[i], u1[i]} + bu;
; #pragma unroll
;             for (int i = 0; i < 4; ++i) bu = bb2[8 + i] * (f32x2){u2[i], u2[i]} + bu;
; #pragma unroll
;             for (int i = 0; i < 4; ++i) bu = bb2[12 + i] * (f32x2){u3[i], u3[i]} + bu;
	v_pk_mul_f32 v[36:37], v[54:55], v[48:49] op_sel:[1,0] op_sel_hi:[0,0]
	v_mov_b32_e32 v33, v35
	v_pk_fma_f32 v[34:35], v[54:55], v[38:39], v[36:37] neg_lo:[0,0,1] neg_hi:[0,0,1]
	v_pk_fma_f32 v[36:37], v[54:55], v[38:39], v[36:37] op_sel_hi:[1,0,1]
	v_pk_mul_f32 v[42:43], v[54:55], v[48:49] op_sel:[1,1] op_sel_hi:[0,1]
	v_mov_b32_e32 v35, v37
	v_pk_fma_f32 v[36:37], v[54:55], v[38:39], v[42:43] op_sel:[0,1,0] neg_lo:[0,0,1] neg_hi:[0,0,1]
	v_pk_fma_f32 v[38:39], v[54:55], v[38:39], v[42:43] op_sel:[0,1,0]
	v_pk_mul_f32 v[42:43], v[54:55], v[50:51] op_sel:[1,0] op_sel_hi:[0,0]
	v_mov_b32_e32 v37, v39
	v_pk_fma_f32 v[38:39], v[54:55], v[40:41], v[42:43] neg_lo:[0,0,1] neg_hi:[0,0,1]
	v_pk_fma_f32 v[42:43], v[54:55], v[40:41], v[42:43] op_sel_hi:[1,0,1]
	v_mov_b32_e32 v16, v51
	v_mov_b32_e32 v39, v43
	v_pk_mul_f32 v[42:43], v[54:55], v[16:17] op_sel:[1,0] op_sel_hi:[0,0]
	v_mov_b32_e32 v16, v41
	v_pk_fma_f32 v[40:41], v[54:55], v[16:17], v[42:43] op_sel_hi:[1,0,1] neg_lo:[0,0,1] neg_hi:[0,0,1]
	v_pk_fma_f32 v[42:43], v[54:55], v[16:17], v[42:43] op_sel_hi:[1,0,1]
	v_pk_mul_f32 v[48:49], v[54:55], v[44:45] op_sel:[1,0] op_sel_hi:[0,0]
	v_mov_b32_e32 v41, v43
	v_pk_fma_f32 v[42:43], v[54:55], v[0:1], v[48:49] neg_lo:[0,0,1] neg_hi:[0,0,1]
	v_pk_fma_f32 v[48:49], v[54:55], v[0:1], v[48:49] op_sel_hi:[1,0,1]
	v_xor_b32_e32 v16, 0x80000000, v17
	v_mov_b32_e32 v43, v49
	v_pk_mul_f32 v[48:49], v[54:55], v[44:45] op_sel:[1,1] op_sel_hi:[0,1]
	v_pk_fma_f32 v[44:45], v[54:55], v[0:1], v[48:49] op_sel:[0,1,0] neg_lo:[0,0,1] neg_hi:[0,0,1]
	v_pk_fma_f32 v[0:1], v[54:55], v[0:1], v[48:49] op_sel:[0,1,0]
	v_pk_mul_f32 v[48:49], v[54:55], v[46:47] op_sel:[1,0] op_sel_hi:[0,0]
	v_mov_b32_e32 v45, v1
	v_pk_fma_f32 v[0:1], v[54:55], v[2:3], v[48:49] neg_lo:[0,0,1] neg_hi:[0,0,1]
	v_pk_fma_f32 v[48:49], v[54:55], v[2:3], v[48:49] op_sel_hi:[1,0,1]
	v_mov_b32_e32 v2, v47
	v_mov_b32_e32 v1, v49
	v_pk_mul_f32 v[48:49], v[54:55], v[2:3] op_sel:[1,0] op_sel_hi:[0,0]
	v_mov_b32_e32 v2, v3
	v_pk_fma_f32 v[46:47], v[54:55], v[2:3], v[48:49] op_sel_hi:[1,0,1] neg_lo:[0,0,1] neg_hi:[0,0,1]
	v_pk_fma_f32 v[2:3], v[54:55], v[2:3], v[48:49] op_sel_hi:[1,0,1]
	v_readfirstlane_b32 s22, v56
	v_readfirstlane_b32 s23, v57
	v_mov_b32_e32 v47, v3
	v_mov_b64_e32 v[2:3], v[144:145]
	v_and_b32_e32 v48, 31, v4
	v_cmp_gt_u32_e32 vcc, 32, v4
	v_mul_u32_u24_e32 v48, 0x1e00, v48
	s_add_u32 s22, s22, s96
	s_addc_u32 s23, s23, s97
	v_cndmask_b32_e64 v49, 0, 16, vcc
	s_waitcnt vmcnt(0)
	global_load_dwordx4 v[128:131], v48, s[22:23]
	global_load_dwordx4 v[132:135], v48, s[22:23] offset:16
	v_permlane32_swap_b32_e32 v18, v20
	v_permlane32_swap_b32_e32 v19, v21
	v_permlane32_swap_b32_e32 v22, v24
	v_permlane32_swap_b32_e32 v23, v25
	v_permlane32_swap_b32_e32 v26, v28
	v_permlane32_swap_b32_e32 v27, v29
	v_permlane32_swap_b32_e32 v30, v32
	v_permlane32_swap_b32_e32 v31, v33
	v_permlane32_swap_b32_e32 v34, v36
	v_permlane32_swap_b32_e32 v35, v37
	v_permlane32_swap_b32_e32 v38, v40
	v_permlane32_swap_b32_e32 v39, v41
	v_permlane32_swap_b32_e32 v42, v44
	v_permlane32_swap_b32_e32 v43, v45
	v_permlane32_swap_b32_e32 v0, v46
	v_permlane32_swap_b32_e32 v1, v47
	s_mov_b32 s7, 0
.Ls51_blk:
	s_add_u32 s22, s22, 0x3c000
	s_addc_u32 s23, s23, 0
	s_waitcnt vmcnt(0)
	v_lshlrev_b32_e32 v56, v49, v128
	v_lshlrev_b32_e32 v57, v49, v129
	v_lshlrev_b32_e32 v58, v49, v130
	v_lshlrev_b32_e32 v59, v49, v131
	v_lshlrev_b32_e32 v60, v49, v132
	v_lshlrev_b32_e32 v61, v49, v133
	v_lshlrev_b32_e32 v62, v49, v134
	v_lshlrev_b32_e32 v63, v49, v135
	v_and_b32_e32 v56, 0xffff0000, v56
	v_and_b32_e32 v57, 0xffff0000, v57
	v_and_b32_e32 v58, 0xffff0000, v58
	v_and_b32_e32 v59, 0xffff0000, v59
	v_and_b32_e32 v60, 0xffff0000, v60
	v_and_b32_e32 v61, 0xffff0000, v61
	v_and_b32_e32 v62, 0xffff0000, v62
	v_and_b32_e32 v63, 0xffff0000, v63
	global_load_dwordx4 v[128:131], v48, s[22:23]
	global_load_dwordx4 v[132:135], v48, s[22:23] offset:16
	v_mfma_f32_32x32x2_f32 v[64:79], v56, v18, 0
	v_mfma_f32_32x32x2_f32 v[80:95], v56, v20, 0
	v_mfma_f32_32x32x2_f32 v[64:79], v57, v22, v[64:79]
	v_mfma_f32_32x32x2_f32 v[80:95], v57, v24, v[80:95]
	v_mfma_f32_32x32x2_f32 v[64:79], v58, v26, v[64:79]
	v_mfma_f32_32x32x2_f32 v[80:95], v58, v28, v[80:95]
	v_mfma_f32_32x32x2_f32 v[64:79], v59, v30, v[64:79]
	v_mfma_f32_32x32x2_f32 v[80:95], v59, v32, v[80:95]
	v_mfma_f32_32x32x2_f32 v[64:79], v60, v34, v[64:79]
	v_mfma_f32_32x32x2_f32 v[80:95], v60, v36, v[80:95]
	v_mfma_f32_32x32x2_f32 v[64:79], v61, v38, v[64:79]
	v_mfma_f32_32x32x2_f32 v[80:95], v61, v40, v[80:95]
	v_mfma_f32_32x32x2_f32 v[64:79], v62, v42, v[64:79]
	v_mfma_f32_32x32x2_f32 v[80:95], v62, v44, v[80:95]
	v_mfma_f32_32x32x2_f32 v[64:79], v63, v0, v[64:79]
	v_mfma_f32_32x32x2_f32 v[80:95], v63, v46, v[80:95]
	v_mfma_f32_32x32x2_f32 v[96:111], v56, v19, 0
	v_mfma_f32_32x32x2_f32 v[112:127], v56, v21, 0
	v_mfma_f32_32x32x2_f32 v[96:111], v57, v23, v[96:111]
	v_mfma_f32_32x32x2_f32 v[112:127], v57, v25, v[112:127]
	v_mfma_f32_32x32x2_f32 v[96:111], v58, v27, v[96:111]
	v_mfma_f32_32x32x2_f32 v[112:127], v58, v29, v[112:127]
	v_mfma_f32_32x32x2_f32 v[96:111], v59, v31, v[96:111]
	v_mfma_f32_32x32x2_f32 v[112:127], v59, v33, v[112:127]
	v_mfma_f32_32x32x2_f32 v[96:111], v60, v35, v[96:111]
	v_mfma_f32_32x32x2_f32 v[112:127], v60, v37, v[112:127]
	v_mfma_f32_32x32x2_f32 v[96:111], v61, v39, v[96:111]
	v_mfma_f32_32x32x2_f32 v[112:127], v61, v41, v[112:127]
	v_mfma_f32_32x32x2_f32 v[96:111], v62, v43, v[96:111]
; #define LAS __attribute__((address_space(3)))
; template <int PASS>
; __device__ __forceinline__ void s5_task(CArgs* Ap, int l, int b, int g, int c, LAS unsigned char* wl, int lane) {
;     ...
;         for (int s = 0; s < 16; ++s) {
;             const f32x4 u0 = *(const LAS f32x4*)(us + s * 16), u1 = *(const LAS f32x4*)(us + s * 16 + 4), u2 = *(const LAS f32x4*)(us + s * 16 + 8), u3 = *(const LAS f32x4*)(us + s * 16 + 12);
;             f32x2 bu = (f32x2){0.f, 0.f};
; #pragma unroll
;             for (int i = 0; i < 4; ++i) bu = bb2[i] * (f32x2){u0[i], u0[i]} + bu;
; #pragma unroll
;             for (int i = 0; i < 4; ++i) bu = bb2[4 + i] * (f32x2){u1[i], u1[i]} + bu;
; #pragma unroll
;             for (int i = 0; i < 4; ++i) bu = bb2[8 + i] * (f32x2){u2[i], u2[i]} + bu;
; #pragma unroll
;             for (int i = 0; i < 4; ++i) bu = bb2[12 + i] * (f32x2){u3[i], u3[i]} + bu;
;             const float br_ = bu.x, bi_ = bu.y;
;             const float nxr = fmaf(ab_re, xr, fmaf(-ab_im, xi, br_)); const float nxi = fmaf(ab_re, xi, fmaf(ab_im, xr, bi_));
;             xr = nxr; xi = nxi;
	v_mfma_f32_32x32x2_f32 v[112:127], v62, v45, v[112:127]
	v_mfma_f32_32x32x2_f32 v[96:111], v63, v1, v[96:111]
	v_mfma_f32_32x32x2_f32 v[112:127], v63, v47, v[112:127]
	s_nop 1
	v_permlane32_swap_b32_e32 v64, v80
	v_permlane32_swap_b32_e32 v65, v81
	v_permlane32_swap_b32_e32 v66, v82
	v_permlane32_swap_b32_e32 v67, v83
	v_permlane32_swap_b32_e32 v68, v84
	v_permlane32_swap_b32_e32 v69, v85
	v_permlane32_swap_b32_e32 v70, v86
	v_permlane32_swap_b32_e32 v71, v87
	v_permlane32_swap_b32_e32 v72, v88
	v_permlane32_swap_b32_e32 v73, v89
	v_permlane32_swap_b32_e32 v74, v90
	v_permlane32_swap_b32_e32 v75, v91
	v_permlane32_swap_b32_e32 v76, v92
	v_permlane32_swap_b32_e32 v77, v93
	v_permlane32_swap_b32_e32 v78, v94
	v_permlane32_swap_b32_e32 v79, v95
	s_nop 1
	v_permlane32_swap_b32_e32 v96, v112
	v_permlane32_swap_b32_e32 v97, v113
	v_permlane32_swap_b32_e32 v98, v114
	v_permlane32_swap_b32_e32 v99, v115
	v_permlane32_swap_b32_e32 v100, v116
	v_permlane32_swap_b32_e32 v101, v117
	v_permlane32_swap_b32_e32 v102, v118
	v_permlane32_swap_b32_e32 v103, v119
	v_permlane32_swap_b32_e32 v104, v120
	v_permlane32_swap_b32_e32 v105, v121
	v_permlane32_swap_b32_e32 v106, v122
	v_permlane32_swap_b32_e32 v107, v123
	v_permlane32_swap_b32_e32 v108, v124
	v_permlane32_swap_b32_e32 v109, v125
	v_permlane32_swap_b32_e32 v110, v126
	v_permlane32_swap_b32_e32 v111, v127
	v_fmac_f32_e32 v64, v16, v3
	v_fmac_f32_e32 v96, v17, v2
	v_fmac_f32_e32 v64, v14, v2
	v_fmac_f32_e32 v96, v14, v3
	v_fmac_f32_e32 v65, v16, v96
	v_fmac_f32_e32 v97, v17, v64
	v_fmac_f32_e32 v65, v14, v64
	v_fmac_f32_e32 v97, v14, v96
	v_fmac_f32_e32 v66, v16, v97
	v_fmac_f32_e32 v98, v17, v65
	v_fmac_f32_e32 v66, v14, v65
	v_fmac_f32_e32 v98, v14, v97
	v_fmac_f32_e32 v67, v16, v98
	v_fmac_f32_e32 v99, v17, v66
	v_fmac_f32_e32 v67, v14, v66
	v_fmac_f32_e32 v99, v14, v98
	v_fmac_f32_e32 v80, v16, v99
	v_fmac_f32_e32 v112, v17, v67
	v_fmac_f32_e32 v80, v14, v67
	v_fmac_f32_e32 v112, v14, v99
	v_fmac_f32_e32 v81, v16, v112
	v_fmac_f32_e32 v113, v17, v80
	v_fmac_f32_e32 v81, v14, v80
	v_fmac_f32_e32 v113, v14, v112
	v_fmac_f32_e32 v82, v16, v113
	v_fmac_f32_e32 v114, v17, v81
	v_fmac_f32_e32 v82, v14, v81
	v_fmac_f32_e32 v114, v14, v113
	v_fmac_f32_e32 v83, v16, v114
	v_fmac_f32_e32 v115, v17, v82
	v_fmac_f32_e32 v83, v14, v82
	v_fmac_f32_e32 v115, v14, v114
	v_fmac_f32_e32 v68, v16, v115
	v_fmac_f32_e32 v100, v17, v83
	v_fmac_f32_e32 v68, v14, v83
	v_fmac_f32_e32 v100, v14, v115
	v_fmac_f32_e32 v69, v16, v100
	v_fmac_f32_e32 v101, v17, v68
	v_fmac_f32_e32 v69, v14, v68
	v_fmac_f32_e32 v101, v14, v100
	v_fmac_f32_e32 v70, v16, v101
	v_fmac_f32_e32 v102, v17, v69
	v_fmac_f32_e32 v70, v14, v69
	v_fmac_f32_e32 v102, v14, v101
	v_fmac_f32_e32 v71, v16, v102
	v_fmac_f32_e32 v103, v17, v70
	v_fmac_f32_e32 v71, v14, v70
	v_fmac_f32_e32 v103, v14, v102
	v_fmac_f32_e32 v84, v16, v103
	v_fmac_f32_e32 v116, v17, v71
	v_fmac_f32_e32 v84, v14, v71
	v_fmac_f32_e32 v116, v14, v103
	v_fmac_f32_e32 v85, v16, v116
	v_fmac_f32_e32 v117, v17, v84
	v_fmac_f32_e32 v85, v14, v84
	v_fmac_f32_e32 v117, v14, v116
	v_fmac_f32_e32 v86, v16, v117
	v_fmac_f32_e32 v118, v17, v85
	v_fmac_f32_e32 v86, v14, v85
	v_fmac_f32_e32 v118, v14, v117
	v_fmac_f32_e32 v87, v16, v118
	v_fmac_f32_e32 v119, v17, v86
	v_fmac_f32_e32 v87, v14, v86
	v_fmac_f32_e32 v119, v14, v118
	v_fmac_f32_e32 v72, v16, v119
	v_fmac_f32_e32 v104, v17, v87
	v_fmac_f32_e32 v72, v14, v87
	v_fmac_f32_e32 v104, v14, v119
	v_fmac_f32_e32 v73, v16, v104
	v_fmac_f32_e32 v105, v17, v72
	v_fmac_f32_e32 v73, v14, v72
	v_fmac_f32_e32 v105, v14, v104
	v_fmac_f32_e32 v74, v16, v105
	v_fmac_f32_e32 v106, v17, v73
	v_fmac_f32_e32 v74, v14, v73
	v_fmac_f32_e32 v106, v14, v105
	v_fmac_f32_e32 v75, v16, v106
	v_fmac_f32_e32 v107, v17, v74
	v_fmac_f32_e32 v75, v14, v74
	v_fmac_f32_e32 v107, v14, v106
	v_fmac_f32_e32 v88, v16, v107
	v_fmac_f32_e32 v120, v17, v75
	v_fmac_f32_e32 v88, v14, v75
	v_fmac_f32_e32 v120, v14, v107
	v_fmac_f32_e32 v89, v16, v120
	v_fmac_f32_e32 v121, v17, v88
	v_fmac_f32_e32 v89, v14, v88
	v_fmac_f32_e32 v121, v14, v120
	v_fmac_f32_e32 v90, v16, v121
	v_fmac_f32_e32 v122, v17, v89
	v_fmac_f32_e32 v90, v14, v89
	v_fmac_f32_e32 v122, v14, v121
	v_fmac_f32_e32 v91, v16, v122
	v_fmac_f32_e32 v123, v17, v90
	v_fmac_f32_e32 v91, v14, v90
	v_fmac_f32_e32 v123, v14, v122
	v_fmac_f32_e32 v76, v16, v123
	v_fmac_f32_e32 v108, v17, v91
	v_fmac_f32_e32 v76, v14, v91
	v_fmac_f32_e32 v108, v14, v123
	v_fmac_f32_e32 v77, v16, v108
	v_fmac_f32_e32 v109, v17, v76
	v_fmac_f32_e32 v77, v14, v76
	v_fmac_f32_e32 v109, v14, v108
	v_fmac_f32_e32 v78, v16, v109
	v_fmac_f32_e32 v110, v17, v77
	v_fmac_f32_e32 v78, v14, v77
	v_fmac_f32_e32 v110, v14, v109
	v_fmac_f32_e32 v79, v16, v110
	v_fmac_f32_e32 v111, v17, v78
	v_fmac_f32_e32 v79, v14, v78
	v_fmac_f32_e32 v111, v14, v110
	v_fmac_f32_e32 v92, v16, v111
	v_fmac_f32_e32 v124, v17, v79
	v_fmac_f32_e32 v92, v14, v79
	v_fmac_f32_e32 v124, v14, v111
	v_fmac_f32_e32 v93, v16, v124
	v_fmac_f32_e32 v125, v17, v92
	v_fmac_f32_e32 v93, v14, v92
	v_fmac_f32_e32 v125, v14, v124
	v_fmac_f32_e32 v94, v16, v125
	v_fmac_f32_e32 v126, v17, v93
	v_fmac_f32_e32 v94, v14, v93
	v_fmac_f32_e32 v126, v14, v125
	v_fmac_f32_e32 v95, v16, v126
	v_fmac_f32_e32 v127, v17, v94
	v_fmac_f32_e32 v95, v14, v94
	v_fmac_f32_e32 v127, v14, v126
	s_add_i32 s7, s7, 1
	v_mov_b32_e32 v2, v95
	v_mov_b32_e32 v3, v127
	s_cmp_lt_u32 s7, 16
	s_cbranch_scc1 .Ls51_blk
	s_waitcnt vmcnt(0)
	s_branch .LBB0_814

; #define LAS __attribute__((address_space(3)))
; template <int MODE>
; __device__ __forceinline__ void softmax_block(f32x4 (&acc)[4], int base, bool ok, int t, int g4, const LAS float* lutg, SmState& st, f32x4 (&O)[4], bf16x8 (&pB)[2]) {
;     float mx = -1e30f; unsigned vm = 0u;
; #pragma unroll
;     for (int nt = 0; nt < 4; ++nt)
; #pragma unroll
;         for (int i = 0; i < 4; ++i) {
;             const int key = base + 16 * nt + 4 * g4 + i;
;             const int dist = (MODE == 0) ? t - (16 * key + 31) : t - key;
;             bool valid = dist >= 0;
;             if (MODE == 1) valid = valid && ok;
;             if (MODE == 2) valid = valid && dist < 512;
;             int dc = dist < 0 ? 0 : dist; dc = dc > 1023 ? 1023 : dc;
;             const float lg = acc[nt][i] + lutg[dc * 4];
;             acc[nt][i] = lg;
;             if (valid) { mx = fmaxf(mx, lg); vm |= 1u << (nt * 4 + i); }
;         }
; __device__ __forceinline__ void nsa_wave(CArgs* Ap, int l, int b, int g, int tq0, const LAS float* lut, LAS float* imp, int lane) {
;     ...
;         for (int jb = jb0; jb <= jb1; ++jb) {
;             bf16x8 kf[4][2]; load_k(kf, Kw + (size_t)jb * 4096, lane);
;             bf16x8 vf[4][2]; load_v(vf, VWT + (size_t)jb * 4096, lane);
;             f32x4 acc[4];
; #pragma unroll
;             for (int nt = 0; nt < 4; ++nt) acc[nt] = (f32x4){0.f, 0.f, 0.f, 0.f};
;             qk_acc(acc, kf, qB);
;             bf16x8 pB[2];
;             softmax_block<2>(acc, jb * 64, true, t, g4, lutg, st, Od, pB);
.Lwin_loop:
	v_mov_b32_e32 v151, 0x1cd
	v_cmp_gt_u32_e32 vcc, v151, v102
	s_cmp_eq_u64 vcc, exec
	s_cselect_b32 s17, 1, 0
	s_cbranch_scc0 .Lwin_lut_gen
	v_lshl_add_u32 v151, v102, 4, v206
	ds_read2_b32 v[244:245], v151 offset0:204 offset1:200
	ds_read2_b32 v[246:247], v151 offset0:196 offset1:192
	ds_read2_b32 v[248:249], v151 offset0:140 offset1:136
	ds_read2_b32 v[250:251], v151 offset0:132 offset1:128
	ds_read2_b32 v[252:253], v151 offset0:76 offset1:72
	ds_read2_b32 v[210:211], v151 offset0:68 offset1:64
	ds_read2_b32 v[212:213], v151 offset0:12 offset1:8
	ds_read_b32 v144, v151 offset:16
	ds_read_b32 v255, v151
	s_branch .Lwin_lut_done

; __device__ __forceinline__ float fexp(float x) { return __expf(x); }
; template <int MODE>
; __device__ __forceinline__ void softmax_block(f32x4 (&acc)[4], int base, bool ok, int t, int g4, const LAS float* lutg, SmState& st, f32x4 (&O)[4], bf16x8 (&pB)[2]) {
;     ...
;             int dc = dist < 0 ? 0 : dist; dc = dc > 1023 ? 1023 : dc;
;             const float lg = acc[nt][i] + lutg[dc * 4];
;             acc[nt][i] = lg;
;             if (valid) { mx = fmaxf(mx, lg); vm |= 1u << (nt * 4 + i); }
;         }
;     mx = fmaxf(mx, __shfl_xor(mx, 16)); mx = fmaxf(mx, __shfl_xor(mx, 32));
;     const float mn = fmaxf(st.m, mx);
;     const float sc = fexp(st.m - mn);
;     float ls = 0.f;
; #pragma unroll
;     for (int nt = 0; nt < 4; ++nt)
; #pragma unroll
;         for (int i = 0; i < 4; ++i) { const float p = ((vm >> (nt * 4 + i)) & 1u) ? fexp(acc[nt][i] - mn) : 0.f; acc[nt][i] = p; ls += p; }
;     st.l = st.l * sc + ls; st.m = mn;
; #pragma unroll
;     for (int dt = 0; dt < 4; ++dt) O[dt] = O[dt] * sc;
; __device__ __forceinline__ void nsa_wave(CArgs* Ap, int l, int b, int g, int tq0, const LAS float* lut, LAS float* imp, int lane) {
;     ...
;             qk_acc(acc, kf, qB);
.Lwin_lut_done:
	v_subrev_u32_e32 v102, 64, v102
	s_add_i32 s0, s0, 1
	s_waitcnt vmcnt(8)
	v_mfma_f32_16x16x32_bf16 v[228:231], v[40:43], v[0:3], 0
	v_mfma_f32_16x16x32_bf16 v[232:235], v[48:51], v[0:3], 0
	v_mfma_f32_16x16x32_bf16 v[236:239], v[56:59], v[0:3], 0
	v_mfma_f32_16x16x32_bf16 v[240:243], v[64:67], v[0:3], 0
	v_mfma_f32_16x16x32_bf16 v[228:231], v[44:47], v[4:7], v[228:231]
	v_mfma_f32_16x16x32_bf16 v[232:235], v[52:55], v[4:7], v[232:235]
	v_mfma_f32_16x16x32_bf16 v[236:239], v[60:63], v[4:7], v[236:239]
	v_mfma_f32_16x16x32_bf16 v[240:243], v[68:71], v[4:7], v[240:243]
	s_cmp_lt_i32 s0, s21
	s_cbranch_scc0 .Lwin_nokpf
	v_lshl_add_u64 v[98:99], v[98:99], 0, s[18:19]
	v_lshl_add_u64 v[124:125], v[124:125], 0, s[18:19]
	global_load_dwordx4 v[40:43], v[98:99], off offset:-4096
	global_load_dwordx4 v[44:47], v[98:99], off offset:-3072
	global_load_dwordx4 v[48:51], v[98:99], off offset:-2048
	global_load_dwordx4 v[52:55], v[98:99], off offset:-1024
	global_load_dwordx4 v[56:59], v[98:99], off offset:0
	global_load_dwordx4 v[60:63], v[98:99], off offset:1024
	global_load_dwordx4 v[64:67], v[98:99], off offset:2048
	global_load_dwordx4 v[68:71], v[98:99], off offset:3072
.Lwin_nokpf:
	s_waitcnt lgkmcnt(0)
	s_nop 7
	v_add_f32_e32 v228, v228, v244
	v_add_f32_e32 v229, v229, v245
	v_add_f32_e32 v230, v230, v246
	v_add_f32_e32 v231, v231, v247
	v_add_f32_e32 v232, v232, v248
	v_add_f32_e32 v233, v233, v249
	v_add_f32_e32 v234, v234, v250
	v_add_f32_e32 v235, v235, v251
	v_add_f32_e32 v236, v236, v252
	v_add_f32_e32 v237, v237, v253
	v_add_f32_e32 v238, v238, v210
	v_add_f32_e32 v239, v239, v211
	v_add_f32_e32 v240, v240, v212
	v_add_f32_e32 v241, v241, v213
	v_add_f32_e32 v242, v242, v144
	v_add_f32_e32 v243, v243, v255
	s_cmp_lg_u32 s17, 0
	s_cbranch_scc0 .Lwin_sm_gen
	v_max3_f32 v244, v228, v229, v230
	v_max3_f32 v247, v231, v232, v233
	v_max3_f32 v250, v234, v235, v236
	v_max3_f32 v253, v237, v238, v239
	v_max3_f32 v212, v240, v241, v242
	v_max3_f32 v244, v244, v247, v250
	v_max3_f32 v253, v253, v212, v243
	v_max_f32_e32 v244, v244, v253
	v_mov_b32_e32 v127, v244
	s_nop 1
	v_permlane16_swap_b32_e32 v244, v127
	v_max_f32_e32 v244, v244, v127
	v_mov_b32_e32 v127, v244
	s_nop 1
	v_permlane32_swap_b32_e32 v244, v127
	v_max3_f32 v214, v103, v244, v127
	v_sub_f32_e32 v150, v103, v214
	v_sub_f32_e32 v228, v228, v214
	v_sub_f32_e32 v229, v229, v214
	v_sub_f32_e32 v230, v230, v214
	v_sub_f32_e32 v231, v231, v214
	v_sub_f32_e32 v232, v232, v214
	v_sub_f32_e32 v233, v233, v214
	v_sub_f32_e32 v234, v234, v214
	v_sub_f32_e32 v235, v235, v214
	v_sub_f32_e32 v236, v236, v214
	v_sub_f32_e32 v237, v237, v214
	v_sub_f32_e32 v238, v238, v214
	v_sub_f32_e32 v239, v239, v214
	v_sub_f32_e32 v240, v240, v214
	v_sub_f32_e32 v241, v241, v214
	v_sub_f32_e32 v242, v242, v214
	v_sub_f32_e32 v243, v243, v214
	v_mul_f32_e32 v150, 0x3fb8aa3b, v150
	v_mul_f32_e32 v228, 0x3fb8aa3b, v228
	v_mul_f32_e32 v229, 0x3fb8aa3b, v229
	v_mul_f32_e32 v230, 0x3fb8aa3b, v230
	v_mul_f32_e32 v231, 0x3fb8aa3b, v231
	v_mul_f32_e32 v232, 0x3fb8aa3b, v232
	v_mul_f32_e32 v233, 0x3fb8aa3b, v233
	v_mul_f32_e32 v234, 0x3fb8aa3b, v234
	v_mul_f32_e32 v235, 0x3fb8aa3b, v235
	v_mul_f32_e32 v236, 0x3fb8aa3b, v236
	v_mul_f32_e32 v237, 0x3fb8aa3b, v237
	v_mul_f32_e32 v238, 0x3fb8aa3b, v238
	v_mul_f32_e32 v239, 0x3fb8aa3b, v239
	v_mul_f32_e32 v240, 0x3fb8aa3b, v240
	v_mul_f32_e32 v241, 0x3fb8aa3b, v241
	v_mul_f32_e32 v242, 0x3fb8aa3b, v242
	v_mul_f32_e32 v243, 0x3fb8aa3b, v243
	v_exp_f32_e32 v150, v150
	v_exp_f32_e32 v228, v228
	v_exp_f32_e32 v229, v229
	v_exp_f32_e32 v230, v230
	v_exp_f32_e32 v231, v231
	v_exp_f32_e32 v232, v232
	v_exp_f32_e32 v233, v233
	v_exp_f32_e32 v234, v234
	v_exp_f32_e32 v235, v235
	v_exp_f32_e32 v236, v236
	v_exp_f32_e32 v237, v237
	v_exp_f32_e32 v238, v238
	v_exp_f32_e32 v239, v239
	v_exp_f32_e32 v240, v240
	v_exp_f32_e32 v241, v241
	v_exp_f32_e32 v242, v242
	v_exp_f32_e32 v243, v243
	v_mov_b32_e32 v103, v214
	s_branch .Lwin_sm_done
; __device__ __forceinline__ unsigned pk2(float lo, float hi) { return pg8::cvt_pk_bf16(lo, hi); }
; __device__ __forceinline__ float fexp(float x) { return __expf(x); }
; template <int MODE>
; __device__ __forceinline__ void softmax_block(f32x4 (&acc)[4], int base, bool ok, int t, int g4, const LAS float* lutg, SmState& st, f32x4 (&O)[4], bf16x8 (&pB)[2]) {
;     ...
;             int dc = dist < 0 ? 0 : dist; dc = dc > 1023 ? 1023 : dc;
;             const float lg = acc[nt][i] + lutg[dc * 4];
;             acc[nt][i] = lg;
;             if (valid) { mx = fmaxf(mx, lg); vm |= 1u << (nt * 4 + i); }
;         }
;     mx = fmaxf(mx, __shfl_xor(mx, 16)); mx = fmaxf(mx, __shfl_xor(mx, 32));
;     const float mn = fmaxf(st.m, mx);
;     const float sc = fexp(st.m - mn);
;     float ls = 0.f;
; #pragma unroll
;     for (int nt = 0; nt < 4; ++nt)
; #pragma unroll
;         for (int i = 0; i < 4; ++i) { const float p = ((vm >> (nt * 4 + i)) & 1u) ? fexp(acc[nt][i] - mn) : 0.f; acc[nt][i] = p; ls += p; }
;     st.l = st.l * sc + ls; st.m = mn;
; #pragma unroll
;     for (int dt = 0; dt < 4; ++dt) O[dt] = O[dt] * sc;
; #pragma unroll
;     for (int hh = 0; hh < 2; ++hh) { u32x4 w; w.x = pk2(acc[2 * hh][0], acc[2 * hh][1]); w.y = pk2(acc[2 * hh][2], acc[2 * hh][3]); w.z = pk2(acc[2 * hh + 1][0], acc[2 * hh + 1][1]); w.w = pk2(acc[2 * hh + 1][2], acc[2 * hh + 1][3]);
;         pB[hh] = __builtin_bit_cast(bf16x8, w); }
; __device__ __forceinline__ void nsa_wave(CArgs* Ap, int l, int b, int g, int tq0, const LAS float* lut, LAS float* imp, int lane) {
;     ...
;             pv_acc(Od, vf, pB);
.Lwin_sm_gen:
	v_cndmask_b32_e64 v244, v182, v228, s[46:47]
	v_cndmask_b32_e64 v245, v182, v229, s[48:49]
	v_cndmask_b32_e64 v246, v182, v230, s[50:51]
	v_cndmask_b32_e64 v247, v182, v231, s[52:53]
	v_cndmask_b32_e64 v248, v182, v232, s[54:55]
	v_cndmask_b32_e64 v249, v182, v233, s[56:57]
	v_cndmask_b32_e64 v250, v182, v234, s[58:59]
	v_cndmask_b32_e64 v251, v182, v235, s[60:61]
	v_cndmask_b32_e64 v252, v182, v236, s[62:63]
	v_cndmask_b32_e64 v253, v182, v237, s[64:65]
	v_cndmask_b32_e64 v210, v182, v238, s[66:67]
	v_cndmask_b32_e64 v211, v182, v239, s[68:69]
	v_cndmask_b32_e64 v212, v182, v240, s[96:97]
	v_cndmask_b32_e64 v213, v182, v241, s[98:99]
	v_cndmask_b32_e64 v144, v182, v242, s[100:101]
	v_cndmask_b32_e64 v255, v182, v243, s[22:23]
	v_max3_f32 v244, v244, v245, v246
	v_max3_f32 v247, v247, v248, v249
	v_max3_f32 v250, v250, v251, v252
	v_max3_f32 v253, v253, v210, v211
	v_max3_f32 v212, v212, v213, v144
	v_max3_f32 v244, v244, v247, v250
	v_max3_f32 v253, v253, v212, v255
	v_max_f32_e32 v244, v244, v253
	v_mov_b32_e32 v127, v244
	s_nop 1
	v_permlane16_swap_b32_e32 v244, v127
	v_max_f32_e32 v244, v244, v127
	v_mov_b32_e32 v127, v244
	s_nop 1
	v_permlane32_swap_b32_e32 v244, v127
	v_max3_f32 v214, v103, v244, v127
	v_sub_f32_e32 v150, v103, v214
	v_sub_f32_e32 v228, v228, v214
	v_sub_f32_e32 v229, v229, v214
	v_sub_f32_e32 v230, v230, v214
	v_sub_f32_e32 v231, v231, v214
	v_sub_f32_e32 v232, v232, v214
	v_sub_f32_e32 v233, v233, v214
	v_sub_f32_e32 v234, v234, v214
	v_sub_f32_e32 v235, v235, v214
	v_sub_f32_e32 v236, v236, v214
	v_sub_f32_e32 v237, v237, v214
	v_sub_f32_e32 v238, v238, v214
	v_sub_f32_e32 v239, v239, v214
	v_sub_f32_e32 v240, v240, v214
	v_sub_f32_e32 v241, v241, v214
	v_sub_f32_e32 v242, v242, v214
	v_sub_f32_e32 v243, v243, v214
	v_mul_f32_e32 v150, 0x3fb8aa3b, v150
	v_mul_f32_e32 v228, 0x3fb8aa3b, v228
	v_mul_f32_e32 v229, 0x3fb8aa3b, v229
	v_mul_f32_e32 v230, 0x3fb8aa3b, v230
	v_mul_f32_e32 v231, 0x3fb8aa3b, v231
	v_mul_f32_e32 v232, 0x3fb8aa3b, v232
	v_mul_f32_e32 v233, 0x3fb8aa3b, v233
	v_mul_f32_e32 v234, 0x3fb8aa3b, v234
	v_mul_f32_e32 v235, 0x3fb8aa3b, v235
	v_mul_f32_e32 v236, 0x3fb8aa3b, v236
	v_mul_f32_e32 v237, 0x3fb8aa3b, v237
	v_mul_f32_e32 v238, 0x3fb8aa3b, v238
	v_mul_f32_e32 v239, 0x3fb8aa3b, v239
	v_mul_f32_e32 v240, 0x3fb8aa3b, v240
	v_mul_f32_e32 v241, 0x3fb8aa3b, v241
	v_mul_f32_e32 v242, 0x3fb8aa3b, v242
	v_mul_f32_e32 v243, 0x3fb8aa3b, v243
	v_exp_f32_e32 v150, v150
	v_exp_f32_e32 v228, v228
	v_exp_f32_e32 v229, v229
	v_exp_f32_e32 v230, v230
	v_exp_f32_e32 v231, v231
	v_exp_f32_e32 v232, v232
	v_exp_f32_e32 v233, v233
	v_exp_f32_e32 v234, v234
	v_exp_f32_e32 v235, v235
	v_exp_f32_e32 v236, v236
	v_exp_f32_e32 v237, v237
	v_exp_f32_e32 v238, v238
	v_exp_f32_e32 v239, v239
	v_exp_f32_e32 v240, v240
	v_exp_f32_e32 v241, v241
	v_exp_f32_e32 v242, v242
	v_exp_f32_e32 v243, v243
	v_mov_b32_e32 v103, v214
	v_cndmask_b32_e64 v228, 0, v228, s[46:47]
	v_cndmask_b32_e64 v229, 0, v229, s[48:49]
	v_cndmask_b32_e64 v230, 0, v230, s[50:51]
	v_cndmask_b32_e64 v231, 0, v231, s[52:53]
	v_cndmask_b32_e64 v232, 0, v232, s[54:55]
	v_cndmask_b32_e64 v233, 0, v233, s[56:57]
	v_cndmask_b32_e64 v234, 0, v234, s[58:59]
	v_cndmask_b32_e64 v235, 0, v235, s[60:61]
	v_cndmask_b32_e64 v236, 0, v236, s[62:63]
	v_cndmask_b32_e64 v237, 0, v237, s[64:65]
	v_cndmask_b32_e64 v238, 0, v238, s[66:67]
	v_cndmask_b32_e64 v239, 0, v239, s[68:69]
	v_cndmask_b32_e64 v240, 0, v240, s[96:97]
	v_cndmask_b32_e64 v241, 0, v241, s[98:99]
	v_cndmask_b32_e64 v242, 0, v242, s[100:101]
	v_cndmask_b32_e64 v243, 0, v243, s[22:23]
.Lwin_sm_done:
	v_pk_mul_f32 v[38:39], v[38:39], v[150:151] op_sel_hi:[1,0]
	v_pk_mul_f32 v[36:37], v[36:37], v[150:151] op_sel_hi:[1,0]
	v_pk_mul_f32 v[34:35], v[34:35], v[150:151] op_sel_hi:[1,0]
	v_pk_mul_f32 v[32:33], v[32:33], v[150:151] op_sel_hi:[1,0]
	v_pk_mul_f32 v[30:31], v[30:31], v[150:151] op_sel_hi:[1,0]
	v_pk_mul_f32 v[28:29], v[28:29], v[150:151] op_sel_hi:[1,0]
	v_pk_mul_f32 v[26:27], v[26:27], v[150:151] op_sel_hi:[1,0]
	v_pk_mul_f32 v[24:25], v[24:25], v[150:151] op_sel_hi:[1,0]
	v_add_f32_e32 v127, v229, v228
	v_add_f32_e32 v127, v230, v127
	v_add_f32_e32 v127, v231, v127
	v_add_f32_e32 v127, v232, v127
	v_add_f32_e32 v127, v233, v127
	v_add_f32_e32 v127, v234, v127
	v_add_f32_e32 v127, v235, v127
	v_add_f32_e32 v127, v236, v127
	v_add_f32_e32 v127, v237, v127
	v_add_f32_e32 v127, v238, v127
	v_add_f32_e32 v127, v239, v127
	v_add_f32_e32 v127, v240, v127
	v_add_f32_e32 v127, v241, v127
	v_add_f32_e32 v127, v242, v127
	v_add_f32_e32 v127, v243, v127
	v_fmac_f32_e32 v127, v126, v150
	v_cvt_pk_bf16_f32 v244, v228, v229
	v_cvt_pk_bf16_f32 v245, v230, v231
	v_cvt_pk_bf16_f32 v246, v232, v233
	v_cvt_pk_bf16_f32 v247, v234, v235
	v_cvt_pk_bf16_f32 v248, v236, v237
	v_cvt_pk_bf16_f32 v249, v238, v239
	v_cvt_pk_bf16_f32 v250, v240, v241
	v_cvt_pk_bf16_f32 v251, v242, v243
	v_mov_b32_e32 v126, v127
	s_cmp_lt_i32 s0, s21
	s_cbranch_scc0 .Lwin_last
	s_waitcnt vmcnt(8)
	v_mfma_f32_16x16x32_bf16 v[36:39], v[72:75], v[244:247], v[36:39]
	v_mfma_f32_16x16x32_bf16 v[32:35], v[80:83], v[244:247], v[32:35]
	v_mfma_f32_16x16x32_bf16 v[28:31], v[108:111], v[244:247], v[28:31]
	v_mfma_f32_16x16x32_bf16 v[24:27], v[116:119], v[244:247], v[24:27]
	v_mfma_f32_16x16x32_bf16 v[36:39], v[76:79], v[248:251], v[36:39]
	v_mfma_f32_16x16x32_bf16 v[32:35], v[104:107], v[248:251], v[32:35]
	v_mfma_f32_16x16x32_bf16 v[28:31], v[112:115], v[248:251], v[28:31]
	v_mfma_f32_16x16x32_bf16 v[24:27], v[120:123], v[248:251], v[24:27]
	global_load_dwordx4 v[72:75], v[124:125], off offset:-4096
	global_load_dwordx4 v[76:79], v[124:125], off offset:-3072
	global_load_dwordx4 v[80:83], v[124:125], off offset:-2048
	global_load_dwordx4 v[104:107], v[124:125], off offset:-1024
	global_load_dwordx4 v[108:111], v[124:125], off offset:0
	global_load_dwordx4 v[112:115], v[124:125], off offset:1024
	global_load_dwordx4 v[116:119], v[124:125], off offset:2048
	global_load_dwordx4 v[120:123], v[124:125], off offset:3072
	s_branch .Lwin_loop
